# combo13 + P1: first row's x loads issued before the shift/scale staging loop (HBM round trip overlaps the staging)
# baseline (speedup 1.0000x reference)
.LBB0_110:
	s_or_b64 exec, exec, s[0:1]
	s_lshr_b32 s0, s11, 19
	s_mul_i32 s1, s0, s3
	s_sub_i32 s1, 0x2000, s1
	s_add_i32 s6, s0, 1
	s_sub_i32 s7, s1, s3
	s_cmp_ge_u32 s1, s3
	s_cselect_b32 s0, s6, s0
	s_cselect_b32 s1, s7, s1
	s_add_i32 s6, s0, 1
	s_cmp_ge_u32 s1, s3
	s_cselect_b32 s0, s6, s0
	s_xor_b32 s0, s0, s10
	s_sub_i32 s3, s0, s10
	s_mul_i32 s16, s3, s2
	s_ashr_i32 s0, s16, 31
	s_lshr_b32 s0, s0, 21
	s_add_i32 s0, s16, s0
	s_ashr_i32 s0, s0, 11
	s_mul_hi_i32 s1, s0, 0xc000
	s_mul_i32 s0, s0, 0xc000
	s_add_u32 s0, s70, s0
	s_addc_u32 s1, s71, s1
	v_lshlrev_b32_e32 v4, 4, v252
	s_waitcnt lgkmcnt(0)
	s_add_u32 s6, s44, 0xffffc000
	v_add_u32_e32 v6, 0, v4
	v_mov_b32_e32 v5, 0
	s_addc_u32 s7, s45, -1
	s_mov_b64 s[8:9], 0
	s_movk_i32 s17, 0x3ff
	s_movk_i32 s18, 0x5ff
	v_mov_b32_e32 v7, v252
	v_readlane_b32 s23, v255, 5
	s_cmp_ge_i32 s23, s3
	s_cbranch_scc1 .Lp1x0_skip
	s_add_i32 s23, s16, s23
	v_mov_b32_e32 v162, s23
	v_mov_b32_e32 v163, 0
	v_lshlrev_b64 v[162:163], 14, v[162:163]
	v_lshlrev_b32_e32 v160, 4, v222
	v_mov_b32_e32 v161, 0
	v_lshl_add_u64 v[160:161], s[36:37], 0, v[160:161]
	v_lshl_add_u64 v[160:161], v[162:163], 0, v[160:161]
	v_add_co_u32_e32 v164, vcc, 0x1000, v160
	s_nop 1
	v_addc_co_u32_e32 v165, vcc, 0, v161, vcc
	v_add_co_u32_e32 v166, vcc, 0x2000, v160
	s_nop 1
	v_addc_co_u32_e32 v167, vcc, 0, v161, vcc
	v_add_co_u32_e32 v168, vcc, 0x3000, v160
	s_nop 1
	v_addc_co_u32_e32 v169, vcc, 0, v161, vcc
	global_load_dwordx4 v[64:67], v[160:161], off nt
	global_load_dwordx4 v[68:71], v[160:161], off offset:1024 nt
	global_load_dwordx4 v[72:75], v[160:161], off offset:2048 nt
	global_load_dwordx4 v[76:79], v[160:161], off offset:3072 nt
	global_load_dwordx4 v[80:83], v[164:165], off nt
	global_load_dwordx4 v[84:87], v[164:165], off offset:1024 nt
	global_load_dwordx4 v[88:91], v[164:165], off offset:2048 nt
	global_load_dwordx4 v[92:95], v[164:165], off offset:3072 nt
	global_load_dwordx4 v[96:99], v[166:167], off nt
	global_load_dwordx4 v[100:103], v[166:167], off offset:1024 nt
	global_load_dwordx4 v[104:107], v[166:167], off offset:2048 nt
	global_load_dwordx4 v[108:111], v[166:167], off offset:3072 nt
	global_load_dwordx4 v[112:115], v[168:169], off nt
	global_load_dwordx4 v[116:119], v[168:169], off offset:1024 nt
	global_load_dwordx4 v[120:123], v[168:169], off offset:2048 nt
	global_load_dwordx4 v[124:127], v[168:169], off offset:3072 nt
.Lp1x0_skip:
	s_branch .LBB0_112

.LBB0_112:
	v_cmp_lt_u32_e32 vcc, s17, v7
	s_and_saveexec_b64 s[10:11], vcc
	v_lshl_add_u64 v[140:141], s[6:7], 0, v[4:5]
	global_load_dwordx4 v[136:139], v[140:141], off
	s_or_b64 exec, exec, s[10:11]
	v_lshl_add_u64 v[132:133], s[0:1], 0, v[4:5]
	v_add_co_u32_e32 v0, vcc, 0x1d000000, v132
	v_lshl_add_u64 v[44:45], s[42:43], 0, v[4:5]
	s_nop 0
	v_addc_co_u32_e32 v1, vcc, 0, v133, vcc
	v_add_co_u32_e32 v8, vcc, 0x1d030000, v132
	s_nop 1
	v_addc_co_u32_e32 v9, vcc, 0, v133, vcc
	v_add_co_u32_e32 v12, vcc, 0x1d060000, v132
	global_load_dwordx4 v[0:3], v[0:1], off
	s_nop 0
	global_load_dwordx4 v[8:11], v[8:9], off
	v_addc_co_u32_e32 v13, vcc, 0, v133, vcc
	v_add_co_u32_e32 v16, vcc, 0x1d090000, v132
	s_nop 1
	v_addc_co_u32_e32 v17, vcc, 0, v133, vcc
	v_add_co_u32_e32 v20, vcc, 0x1d0c0000, v132
	global_load_dwordx4 v[12:15], v[12:13], off
	s_nop 0
	global_load_dwordx4 v[16:19], v[16:17], off
	v_addc_co_u32_e32 v21, vcc, 0, v133, vcc
	v_add_co_u32_e32 v24, vcc, 0x1d0f0000, v132
	s_nop 1
	v_addc_co_u32_e32 v25, vcc, 0, v133, vcc
	v_add_co_u32_e32 v28, vcc, 0x1d120000, v132
	global_load_dwordx4 v[20:23], v[20:21], off
	s_nop 0
	global_load_dwordx4 v[24:27], v[24:25], off
	v_addc_co_u32_e32 v29, vcc, 0, v133, vcc
	v_add_co_u32_e32 v32, vcc, 0x1d150000, v132
	s_nop 1
	v_addc_co_u32_e32 v33, vcc, 0, v133, vcc
	v_add_co_u32_e32 v36, vcc, 0x1d180000, v132
	global_load_dwordx4 v[28:31], v[28:29], off
	s_nop 0
	global_load_dwordx4 v[32:35], v[32:33], off
	v_addc_co_u32_e32 v37, vcc, 0, v133, vcc
	v_add_co_u32_e32 v40, vcc, 0x1d1b0000, v132
	s_nop 1
	v_addc_co_u32_e32 v41, vcc, 0, v133, vcc
	global_load_dwordx4 v[36:39], v[36:37], off
	s_nop 0
	global_load_dwordx4 v[40:43], v[40:41], off
	v_add_co_u32_e32 v48, vcc, 0x1d1e0000, v132
	global_load_dwordx4 v[44:47], v[44:45], off
	s_nop 0
	v_addc_co_u32_e32 v49, vcc, 0, v133, vcc
	v_add_co_u32_e32 v52, vcc, 0x1d210000, v132
	s_nop 1
	v_addc_co_u32_e32 v53, vcc, 0, v133, vcc
	v_add_co_u32_e32 v56, vcc, 0x1d240000, v132
	global_load_dwordx4 v[48:51], v[48:49], off
	s_nop 0
	global_load_dwordx4 v[52:55], v[52:53], off
	v_addc_co_u32_e32 v57, vcc, 0, v133, vcc
	v_add_co_u32_e32 v60, vcc, 0x1d270000, v132
	s_nop 0
	s_nop 0
	v_addc_co_u32_e32 v61, vcc, 0, v133, vcc
	v_add_co_u32_e32 v128, vcc, 0x1d2a0000, v132
	global_load_dwordx4 v[56:59], v[56:57], off
	s_nop 0
	global_load_dwordx4 v[60:63], v[60:61], off
	v_addc_co_u32_e32 v129, vcc, 0, v133, vcc
	v_add_co_u32_e32 v132, vcc, 0x1d2d0000, v132
	global_load_dwordx4 v[128:131], v[128:129], off
	s_nop 0
	v_addc_co_u32_e32 v133, vcc, 0, v133, vcc
	global_load_dwordx4 v[132:135], v[132:133], off
	s_waitcnt vmcnt(6)
	v_pk_add_f32 v[2:3], v[46:47], v[2:3]
	v_pk_add_f32 v[0:1], v[44:45], v[0:1]
	v_pk_add_f32 v[2:3], v[2:3], v[10:11]
	v_pk_add_f32 v[0:1], v[0:1], v[8:9]
	v_pk_add_f32 v[2:3], v[2:3], v[14:15]
	v_pk_add_f32 v[0:1], v[0:1], v[12:13]
	v_pk_add_f32 v[2:3], v[2:3], v[18:19]
	v_pk_add_f32 v[0:1], v[0:1], v[16:17]
	v_pk_add_f32 v[2:3], v[2:3], v[22:23]
	v_pk_add_f32 v[0:1], v[0:1], v[20:21]
	v_pk_add_f32 v[2:3], v[2:3], v[26:27]
	v_pk_add_f32 v[0:1], v[0:1], v[24:25]
	v_pk_add_f32 v[2:3], v[2:3], v[30:31]
	v_pk_add_f32 v[0:1], v[0:1], v[28:29]
	v_pk_add_f32 v[2:3], v[2:3], v[34:35]
	v_pk_add_f32 v[0:1], v[0:1], v[32:33]
	v_pk_add_f32 v[2:3], v[2:3], v[38:39]
	v_pk_add_f32 v[0:1], v[0:1], v[36:37]
	v_pk_add_f32 v[2:3], v[2:3], v[42:43]
	v_pk_add_f32 v[0:1], v[0:1], v[40:41]
	v_cmp_lt_u32_e32 vcc, s17, v7
	s_waitcnt vmcnt(5)
	v_pk_add_f32 v[2:3], v[2:3], v[50:51]
	v_pk_add_f32 v[0:1], v[0:1], v[48:49]
	s_waitcnt vmcnt(4)
	v_pk_add_f32 v[2:3], v[2:3], v[54:55]
	v_pk_add_f32 v[0:1], v[0:1], v[52:53]
	s_waitcnt vmcnt(3)
	v_pk_add_f32 v[2:3], v[2:3], v[58:59]
	v_pk_add_f32 v[0:1], v[0:1], v[56:57]
	s_waitcnt vmcnt(2)
	v_pk_add_f32 v[2:3], v[2:3], v[62:63]
	v_pk_add_f32 v[0:1], v[0:1], v[60:61]
	s_waitcnt vmcnt(1)
	v_pk_add_f32 v[2:3], v[2:3], v[130:131]
	v_pk_add_f32 v[0:1], v[0:1], v[128:129]
	s_waitcnt vmcnt(0)
	v_pk_add_f32 v[2:3], v[2:3], v[134:135]
	v_pk_add_f32 v[0:1], v[0:1], v[132:133]
	s_and_saveexec_b64 s[10:11], vcc
	s_cbranch_execz .LBB0_111
	v_pk_add_f32 v[2:3], v[2:3], 1.0 op_sel_hi:[1,0]
	v_pk_add_f32 v[0:1], v[0:1], 1.0 op_sel_hi:[1,0]
	s_waitcnt vmcnt(0)
	v_pk_mul_f32 v[2:3], v[2:3], v[138:139]
	v_pk_mul_f32 v[0:1], v[0:1], v[136:137]
	s_branch .LBB0_111

.Lp1mod_done:
	s_or_b64 exec, exec, s[26:27]
	v_readlane_b32 s0, v255, 5
	s_cmp_ge_i32 s0, s3
	s_waitcnt lgkmcnt(0)
	s_barrier
	s_cbranch_scc1 .LBB0_117
	v_mov_b32_e32 v1, 0
	v_lshlrev_b32_e32 v2, 3, v222
	v_mov_b32_e32 v3, v1
	v_lshl_add_u64 v[26:27], s[14:15], 0, v[2:3]
	v_lshlrev_b32_e32 v2, 2, v222
	v_lshlrev_b32_e32 v0, 4, v222
	v_lshl_add_u64 v[2:3], s[70:71], 0, v[2:3]
	s_mov_b64 s[0:1], 0x1f800000
	v_lshl_add_u64 v[24:25], s[36:37], 0, v[0:1]
	v_lshl_add_u64 v[28:29], v[2:3], 0, s[0:1]
	v_add_u32_e32 v36, 0, v0
	s_movk_i32 s6, 0x1000
	s_movk_i32 s7, 0x2000
	s_movk_i32 s8, 0x3000
	v_mov_b32_e32 v37, 0x358637bd
	s_mov_b32 s9, 0xf800000
	v_mov_b32_e32 v38, 0x260
	s_mov_b32 s10, 0xc3e00000
	v_mov_b32_e32 v39, 0x43e00000
	v_readlane_b32 s11, v255, 5
	s_mov_b64 s[26:27], 0x1000
	s_mov_b64 s[30:31], 0x2000
	s_mov_b64 s[34:35], 0x3000
.LBB0_116:
	s_add_i32 s0, s16, s11
	s_ashr_i32 s1, s0, 31
	s_lshl_b64 s[18:19], s[0:1], 14
	ds_read_b128 v[4:7], v36
	ds_read_b128 v[0:3], v36 offset:1024
	ds_read_b128 v[12:15], v36 offset:16384
	ds_read_b128 v[8:11], v36 offset:17408
	ds_read_b128 v[16:19], v36 offset:2048
	ds_read_b128 v[20:23], v36 offset:3072
	ds_read_b128 v[56:59], v36 offset:18432
	ds_read_b128 v[60:63], v36 offset:19456
	s_lshl_b64 s[20:21], s[0:1], 12
	s_nop 0
	s_lshl_b64 s[0:1], s[0:1], 13
	s_nop 0
	v_lshl_add_u64 v[34:35], v[26:27], 0, s[0:1]
	s_nop 0
	s_nop 0
	s_nop 0
	s_nop 0
	s_nop 0
	s_nop 0
	v_add_co_u32_e32 v32, vcc, s6, v34
	v_mov_b32_e32 v40, 0
	s_nop 0
	v_addc_co_u32_e32 v33, vcc, 0, v35, vcc
	v_mov_b32_e32 v41, 0
	v_mov_b32_e32 v43, 0
	v_mov_b32_e32 v45, 0
	v_lshl_add_u64 v[30:31], v[28:29], 0, s[20:21]
	v_mov_b32_e32 v42, 0
	v_mov_b32_e32 v44, 0
	v_mov_b32_e32 v47, 0
	v_mov_b32_e32 v49, 0
	v_mov_b32_e32 v46, 0
	v_mov_b32_e32 v48, 0
	v_mov_b32_e32 v51, 0
	v_mov_b32_e32 v53, 0
	v_mov_b32_e32 v50, 0
	v_mov_b32_e32 v52, 0
	v_mov_b32_e32 v54, 0
	v_mov_b32_e32 v55, 0
	s_add_i32 s11, s11, 8
	s_add_i32 s23, s16, s11
	s_cmp_lt_i32 s11, s3
	v_mov_b32_e32 v162, s23
	v_mov_b32_e32 v163, 0
	v_lshlrev_b64 v[162:163], 14, v[162:163]
	v_lshl_add_u64 v[160:161], v[162:163], 0, v[24:25]
	v_lshl_add_u64 v[164:165], v[160:161], 0, s[26:27]
	v_lshl_add_u64 v[166:167], v[160:161], 0, s[30:31]
	v_lshl_add_u64 v[168:169], v[160:161], 0, s[34:35]
	s_waitcnt vmcnt(15)
	v_mul_f32_e32 v128, v65, v65
	v_mul_f32_e32 v129, v67, v67
	s_waitcnt vmcnt(14)
	v_mul_f32_e32 v130, v69, v69
	v_mul_f32_e32 v131, v71, v71
	s_waitcnt vmcnt(13)
	v_mul_f32_e32 v132, v73, v73
	v_mul_f32_e32 v133, v75, v75
	v_fmac_f32_e32 v128, v64, v64
	v_fmac_f32_e32 v129, v66, v66
	v_fmac_f32_e32 v130, v68, v68
	v_fmac_f32_e32 v131, v70, v70
	s_waitcnt vmcnt(12)
	v_mul_f32_e32 v134, v77, v77
	v_mul_f32_e32 v135, v79, v79
	v_fmac_f32_e32 v132, v72, v72
	v_fmac_f32_e32 v133, v74, v74
	v_add_f32_e32 v128, v128, v129
	v_add_f32_e32 v129, v130, v131
	v_fmac_f32_e32 v134, v76, v76
	v_fmac_f32_e32 v135, v78, v78
	s_waitcnt vmcnt(11)
	v_mul_f32_e32 v136, v81, v81
	v_mul_f32_e32 v137, v83, v83
	v_add_f32_e32 v130, v132, v133
	v_add_f32_e32 v128, v128, v129
	s_waitcnt vmcnt(10)
	v_mul_f32_e32 v138, v85, v85
	v_mul_f32_e32 v139, v87, v87
	v_add_f32_e32 v131, v134, v135
	v_fmac_f32_e32 v136, v80, v80
	v_fmac_f32_e32 v137, v82, v82
	v_add_f32_e32 v128, v128, v130
	s_waitcnt vmcnt(9)
	v_mul_f32_e32 v140, v89, v89
	v_mul_f32_e32 v141, v91, v91
	v_fmac_f32_e32 v138, v84, v84
	v_fmac_f32_e32 v139, v86, v86
	v_add_f32_e32 v129, v136, v137
	v_add_f32_e32 v128, v128, v131
	s_waitcnt vmcnt(8)
	v_mul_f32_e32 v142, v93, v93
	v_mul_f32_e32 v143, v95, v95
	v_fmac_f32_e32 v140, v88, v88
	v_fmac_f32_e32 v141, v90, v90
	v_add_f32_e32 v132, v138, v139
	v_add_f32_e32 v128, v128, v129
	s_waitcnt vmcnt(7)
	v_mul_f32_e32 v144, v97, v97
	v_mul_f32_e32 v145, v99, v99
	v_fmac_f32_e32 v142, v92, v92
	v_fmac_f32_e32 v143, v94, v94
	v_add_f32_e32 v133, v140, v141
	v_add_f32_e32 v128, v128, v132
	s_waitcnt vmcnt(6)
	v_mul_f32_e32 v146, v101, v101
	v_mul_f32_e32 v147, v103, v103
	v_fmac_f32_e32 v144, v96, v96
	v_fmac_f32_e32 v145, v98, v98
	v_add_f32_e32 v134, v142, v143
	v_add_f32_e32 v128, v128, v133
	s_waitcnt vmcnt(5)
	v_mul_f32_e32 v148, v105, v105
	v_mul_f32_e32 v149, v107, v107
	v_fmac_f32_e32 v146, v100, v100
	v_fmac_f32_e32 v147, v102, v102
	v_add_f32_e32 v135, v144, v145
	v_add_f32_e32 v128, v128, v134
	s_waitcnt vmcnt(4)
	v_mul_f32_e32 v150, v109, v109
	v_mul_f32_e32 v151, v111, v111
	v_fmac_f32_e32 v148, v104, v104
	v_fmac_f32_e32 v149, v106, v106
	v_add_f32_e32 v136, v146, v147
	v_add_f32_e32 v128, v128, v135
	s_waitcnt vmcnt(3)
	v_mul_f32_e32 v152, v113, v113
	v_mul_f32_e32 v153, v115, v115
	v_fmac_f32_e32 v150, v108, v108
	v_fmac_f32_e32 v151, v110, v110
	v_add_f32_e32 v137, v148, v149
	v_add_f32_e32 v128, v128, v136
	s_waitcnt vmcnt(2)
	v_mul_f32_e32 v154, v117, v117
	v_mul_f32_e32 v155, v119, v119
	v_fmac_f32_e32 v152, v112, v112
	v_fmac_f32_e32 v153, v114, v114
	v_add_f32_e32 v138, v150, v151
	v_add_f32_e32 v128, v128, v137
	s_waitcnt vmcnt(1)
	v_mul_f32_e32 v156, v121, v121
	v_mul_f32_e32 v157, v123, v123
	v_fmac_f32_e32 v154, v116, v116
	v_fmac_f32_e32 v155, v118, v118
	v_add_f32_e32 v139, v152, v153
	v_add_f32_e32 v128, v128, v138
	s_waitcnt vmcnt(0)
	v_mul_f32_e32 v158, v125, v125
	v_mul_f32_e32 v159, v127, v127
	v_fmac_f32_e32 v156, v120, v120
	v_fmac_f32_e32 v157, v122, v122
	v_add_f32_e32 v140, v154, v155
	v_add_f32_e32 v128, v128, v139
	v_fmac_f32_e32 v158, v124, v124
	v_fmac_f32_e32 v159, v126, v126
	v_add_f32_e32 v141, v156, v157
	v_add_f32_e32 v128, v128, v140
	v_add_f32_e32 v142, v158, v159
	v_add_f32_e32 v128, v128, v141
	v_add_f32_e32 v128, v128, v142
	s_nop 1
	v_add_f32_dpp v128, v128, v128 quad_perm:[1,0,3,2] row_mask:0xf bank_mask:0xf bound_ctrl:1
	s_nop 1
	v_add_f32_dpp v128, v128, v128 quad_perm:[2,3,0,1] row_mask:0xf bank_mask:0xf bound_ctrl:1
	s_nop 1
	v_add_f32_dpp v128, v128, v128 row_half_mirror row_mask:0xf bank_mask:0xf bound_ctrl:1
	s_nop 1
	v_add_f32_dpp v128, v128, v128 row_mirror row_mask:0xf bank_mask:0xf bound_ctrl:1
	v_mov_b32_e32 v129, v128
	s_nop 1
	v_permlane16_swap_b32_e32 v128, v129
	v_add_f32_e32 v128, v128, v129
	v_mov_b32_e32 v129, v128
	s_nop 1
	v_permlane32_swap_b32_e32 v128, v129
	v_add_f32_e32 v128, v128, v129
	v_fmamk_f32 v128, v128, 0x39800000, v37
	v_mul_f32_e32 v129, 0x4f800000, v128
	v_cmp_gt_f32_e32 vcc, s9, v128
	s_nop 1
	v_cndmask_b32_e32 v128, v128, v129, vcc
	v_sqrt_f32_e32 v129, v128
	s_nop 0
	v_add_u32_e32 v130, -1, v129
	v_add_u32_e32 v131, 1, v129
	v_fma_f32 v132, -v130, v129, v128
	v_fma_f32 v133, -v131, v129, v128
	v_cmp_ge_f32_e64 s[0:1], 0, v132
	s_nop 1
	v_cndmask_b32_e64 v129, v129, v130, s[0:1]
	v_cmp_lt_f32_e64 s[0:1], 0, v133
	s_nop 1
	v_cndmask_b32_e64 v129, v129, v131, s[0:1]
	v_mul_f32_e32 v130, 0x37800000, v129
	v_cndmask_b32_e32 v129, v129, v130, vcc
	v_cmp_class_f32_e32 vcc, v128, v38
	s_nop 1
	v_cndmask_b32_e32 v128, v129, v128, vcc
	v_div_scale_f32 v129, s[0:1], v128, v128, 1.0
	v_rcp_f32_e32 v131, v129
	v_div_scale_f32 v130, vcc, 1.0, v128, 1.0
	v_fma_f32 v132, -v129, v131, 1.0
	v_fmac_f32_e32 v131, v132, v131
	v_mul_f32_e32 v132, v130, v131
	v_fma_f32 v133, -v129, v132, v130
	v_fmac_f32_e32 v132, v133, v131
	v_fma_f32 v129, -v129, v132, v130
	v_div_fmas_f32 v129, v129, v131, v132
	v_div_fixup_f32 v128, v129, v128, 1.0
	v_pk_mul_f32 v[64:65], v[128:129], v[64:65] op_sel_hi:[0,1]
	v_pk_mul_f32 v[66:67], v[128:129], v[66:67] op_sel_hi:[0,1]
	v_pk_mul_f32 v[68:69], v[128:129], v[68:69] op_sel_hi:[0,1]
	v_pk_mul_f32 v[70:71], v[128:129], v[70:71] op_sel_hi:[0,1]
	v_pk_mul_f32 v[72:73], v[128:129], v[72:73] op_sel_hi:[0,1]
	v_pk_mul_f32 v[74:75], v[128:129], v[74:75] op_sel_hi:[0,1]
	s_waitcnt lgkmcnt(5)
	v_pk_fma_f32 v[6:7], v[14:15], v[66:67], v[6:7]
	v_pk_fma_f32 v[4:5], v[12:13], v[64:65], v[4:5]
	s_waitcnt lgkmcnt(4)
	v_pk_fma_f32 v[2:3], v[10:11], v[70:71], v[2:3]
	v_pk_fma_f32 v[0:1], v[8:9], v[68:69], v[0:1]
	s_waitcnt lgkmcnt(1)
	v_pk_fma_f32 v[8:9], v[58:59], v[74:75], v[18:19]
	v_pk_fma_f32 v[10:11], v[56:57], v[72:73], v[16:17]
	v_cvt_pk_f16_f32 v16, v4, v5
	v_cvt_pk_f16_f32 v17, v6, v7
	v_mul_f32_e32 v18, 0x41800000, v4
	v_mul_f32_e32 v19, 0x41800000, v5
	v_pk_mul_f32 v[76:77], v[128:129], v[76:77] op_sel_hi:[0,1]
	global_store_dwordx2 v[34:35], v[16:17], off
	v_med3_f32 v16, v18, s10, v39
	v_med3_f32 v17, v19, s10, v39
	s_waitcnt lgkmcnt(0)
	v_pk_fma_f32 v[14:15], v[60:61], v[76:77], v[20:21]
	v_mul_f32_e32 v20, 0x41800000, v0
	v_mul_f32_e32 v21, 0x41800000, v1
	v_cvt_pk_fp8_f32 v40, v16, v17
	v_pk_mul_f32 v[78:79], v[128:129], v[78:79] op_sel_hi:[0,1]
	v_med3_f32 v18, v20, s10, v39
	v_med3_f32 v19, v21, s10, v39
	v_pk_fma_f32 v[12:13], v[62:63], v[78:79], v[22:23]
	v_mul_f32_e32 v6, 0x41800000, v6
	v_mul_f32_e32 v7, 0x41800000, v7
	v_cvt_pk_f16_f32 v4, v0, v1
	v_cvt_pk_f16_f32 v5, v2, v3
	v_mul_f32_e32 v22, 0x41800000, v2
	v_cvt_pk_f16_f32 v0, v10, v11
	v_mul_f32_e32 v10, 0x41800000, v10
	v_mul_f32_e32 v11, 0x41800000, v11
	v_cvt_pk_f16_f32 v2, v14, v15
	v_mul_f32_e32 v14, 0x41800000, v14
	v_mul_f32_e32 v15, 0x41800000, v15
	v_cvt_pk_fp8_f32 v41, v18, v19
	v_med3_f32 v6, v6, s10, v39
	v_med3_f32 v7, v7, s10, v39
	v_med3_f32 v10, v10, s10, v39
	v_med3_f32 v11, v11, s10, v39
	v_med3_f32 v14, v14, s10, v39
	v_med3_f32 v15, v15, s10, v39
	v_mul_f32_e32 v23, 0x41800000, v3
	v_cvt_pk_fp8_f32 v43, v10, v11
	v_cvt_pk_fp8_f32 v45, v14, v15
	v_cvt_pk_fp8_f32 v40, v6, v7 op_sel:[0,0,1]
	v_med3_f32 v20, v22, s10, v39
	v_med3_f32 v21, v23, s10, v39
	v_cvt_pk_f16_f32 v1, v8, v9
	v_mul_f32_e32 v8, 0x41800000, v8
	v_mul_f32_e32 v9, 0x41800000, v9
	v_cvt_pk_f16_f32 v3, v12, v13
	v_mul_f32_e32 v12, 0x41800000, v12
	v_mul_f32_e32 v13, 0x41800000, v13
	v_cvt_pk_fp8_f32 v41, v20, v21 op_sel:[0,0,1]
	v_med3_f32 v8, v8, s10, v39
	v_med3_f32 v9, v9, s10, v39
	v_med3_f32 v12, v12, s10, v39
	v_med3_f32 v13, v13, s10, v39
	v_cvt_pk_fp8_f32 v43, v8, v9 op_sel:[0,0,1]
	v_cvt_pk_fp8_f32 v45, v12, v13 op_sel:[0,0,1]
	global_store_dword v[30:31], v40, off
	global_store_dwordx2 v[34:35], v[4:5], off offset:512
	global_store_dword v[30:31], v41, off offset:256
	global_store_dwordx2 v[34:35], v[0:1], off offset:1024
	global_store_dword v[30:31], v43, off offset:512
	global_store_dwordx2 v[34:35], v[2:3], off offset:1536
	global_store_dword v[30:31], v45, off offset:768
	s_cbranch_scc0 .Lp1_nopf0
	global_load_dwordx4 v[64:67], v[160:161], off nt
	global_load_dwordx4 v[68:71], v[160:161], off offset:1024 nt
	global_load_dwordx4 v[72:75], v[160:161], off offset:2048 nt
	global_load_dwordx4 v[76:79], v[160:161], off offset:3072 nt
